# q/k RMS-norm+rope epilogue rewritten by hand with scalar f32 VALU (no packed f32), rope rows from LDS table, same op order
# baseline (speedup 1.0000x reference)
.LBB0_504:
	s_movk_i32 s11, 0x7fe0
	v_cmp_gt_i32_e64 s[48:49], s11, v146
	s_movk_i32 s11, 0x7fd0
	v_cmp_gt_i32_e64 s[46:47], s11, v146
	s_movk_i32 s11, 0x7f80
	v_cmp_gt_i32_e64 s[44:45], s11, v146
	s_movk_i32 s11, 0x7f70
	v_bfe_i32 v33, v147, 4, 1
	s_and_b64 vcc, exec, s[0:1]
	s_mov_b32 s0, 0x8000
	v_cmp_gt_i32_e64 s[42:43], s11, v146
	s_movk_i32 s11, 0x7f60
	v_lshlrev_b32_e32 v32, 2, v148
	v_and_b32_e32 v33, 12, v33
	v_cmp_gt_i32_e64 s[52:53], s0, v146
	s_movk_i32 s0, 0x7ff0
	v_add_u32_e32 v152, 0x90, v146
	v_cmp_gt_i32_e64 s[40:41], s11, v146
	s_movk_i32 s11, 0x7f50
	s_lshl_b32 s21, s21, 5
	v_lshlrev_b32_e32 v150, 2, v162
	v_or_b32_e32 v150, 0x20010, v150
	v_or_b32_e32 v158, 16, v146
	v_cmp_gt_i32_e64 s[0:1], s0, v146
	v_or_b32_e32 v156, 32, v146
	v_or_b32_e32 v155, 48, v146
	v_add_u32_e32 v153, 0x80, v146
	v_lshlrev_b32_e32 v161, 2, v32
	v_lshlrev_b32_e32 v138, 1, v32
	v_lshlrev_b32_e32 v136, 1, v33
	v_bitop3_b32 v160, v146, 31, 16 bitop3:0xc8
	v_bitop3_b32 v159, v146, 47, 32 bitop3:0xc8
	v_bitop3_b32 v157, v146, 63, 48 bitop3:0xc8
	v_and_b32_e32 v154, 31, v152
	v_add_u32_e32 v151, 0xa0, v146
	v_add_u32_e32 v149, 0xb0, v146
	v_cmp_gt_i32_e64 s[38:39], s11, v146
	s_cbranch_vccz .LBB0_506
	s_cmpk_lt_i32 s3, 0x400
	s_cselect_b32 s28, 0x3e38aa3b, 1.0
	s_mov_b32 s27, 0x22110
	s_cselect_b32 s27, 0x22010, s27
	s_lshl_b32 s26, s21, 2
	s_add_u32 s27, s27, s26
	v_add_u32_e32 v246, s27, v161
	ds_read_b128 v[184:187], v246
	ds_read_b128 v[188:191], v246 offset:64
	s_lshl_b32 s0, s20, 8
	v_or_b32_e32 v246, s0, v141
	v_bitop3_b32 v247, s0, v231, v141 bitop3:0x36
	v_lshlrev_b32_e32 v246, 2, v246
	v_lshlrev_b32_e32 v247, 2, v247
	v_add_u32_e32 v246, 0xc000, v246
	v_add_u32_e32 v247, 0xc000, v247
	ds_read2_b32 v[222:223], v246 offset0:0 offset1:16
	ds_read2_b32 v[238:239], v247 offset0:0 offset1:16
	ds_read2_b32 v[224:225], v246 offset0:32 offset1:48
	ds_read2_b32 v[240:241], v247 offset0:32 offset1:48
	ds_read2_b32 v[226:227], v246 offset0:128 offset1:144
	ds_read2_b32 v[242:243], v247 offset0:128 offset1:144
	ds_read2_b32 v[228:229], v246 offset0:160 offset1:176
	ds_read2_b32 v[244:245], v247 offset0:160 offset1:176
	s_cmp_lt_i32 s18, 0x8000
	s_movk_i32 s29, 0xfc0
	s_cselect_b32 s29, 0x7c0, s29
	s_cmp_eq_u32 s21, 0
	s_cbranch_scc0 .Lq0_odd
	s_and_b32 s0, s18, s29
	s_lshl_b32 s0, s0, 1
	s_add_i32 s1, s18, 0x80
	s_and_b32 s1, s1, s29
	s_lshl_b32 s1, s1, 1
	v_add_u32_e32 v192, s0, v150
	v_add_u32_e32 v193, s0, v150
	v_add_u32_e32 v194, s0, v150
	v_add_u32_e32 v195, s0, v150
	v_add_u32_e32 v196, s1, v150
	v_add_u32_e32 v197, s1, v150
	v_add_u32_e32 v198, s1, v150
	v_add_u32_e32 v199, s1, v150
	s_branch .Lq0_rows
.Lq0_odd:
	v_lshlrev_b32_e32 v246, 7, v141
	v_add_u32_e32 v192, v246, v150
	v_add_u32_e32 v193, 0x800, v192
	v_add_u32_e32 v194, 0x1000, v192
	v_add_u32_e32 v195, 0x1800, v192
	v_mov_b32_e32 v196, v192
	v_mov_b32_e32 v197, v193
	v_mov_b32_e32 v198, v194
	v_mov_b32_e32 v199, v195
.Lq0_rows:
	ds_read_b128 v[200:203], v192
	ds_read_b128 v[204:207], v192 offset:16
	v_mul_u32_u24_e32 v246, s33, v146
	v_add3_u32 v246, v246, v138, v136
	s_lshl_b32 s0, s10, 1
	v_add_u32_e32 v246, s0, v246
	v_mov_b32_e32 v209, s93
	v_add_co_u32_e32 v208, vcc, s92, v246
	s_nop 1
	v_addc_co_u32_e32 v209, vcc, 0, v209, vcc
	s_mov_b32 vcc_lo, 0x12000
	s_mov_b32 vcc_hi, 0
	s_mov_b32 s26, 0x3c800000
	s_waitcnt lgkmcnt(0)
	ds_read_b128 v[214:217], v193
	ds_read_b128 v[218:221], v193 offset:16
	v_add_f32_e32 v246, v238, v222
	v_fma_f32 v246, v246, s26, v230
	v_rsq_f32_e32 v246, v246
	v_lshl_add_u64 v[248:249], vcc, 0, v[208:209]
	v_mul_f32_e32 v120, v120, v246
	v_mul_f32_e32 v121, v121, v246
	v_mul_f32_e32 v122, v122, v246
	v_mul_f32_e32 v123, v123, v246
	v_mul_f32_e32 v124, v124, v246
	v_mul_f32_e32 v125, v125, v246
	v_mul_f32_e32 v126, v126, v246
	v_mul_f32_e32 v127, v127, v246
	v_mul_f32_e32 v120, v184, v120
	v_mul_f32_e32 v121, v185, v121
	v_mul_f32_e32 v122, v186, v122
	v_mul_f32_e32 v123, v187, v123
	v_mul_f32_e32 v124, v188, v124
	v_mul_f32_e32 v125, v189, v125
	v_mul_f32_e32 v126, v190, v126
	v_mul_f32_e32 v127, v191, v127
	v_mul_f32_e32 v246, v201, v124
	v_mul_f32_e32 v247, v200, v124
	v_fma_f32 v124, v201, v120, v247
	v_fma_f32 v120, v200, v120, -v246
	v_mul_f32_e32 v246, v203, v125
	v_mul_f32_e32 v247, v202, v125
	v_fma_f32 v125, v203, v121, v247
	v_fma_f32 v121, v202, v121, -v246
	v_mul_f32_e32 v246, v205, v126
	v_mul_f32_e32 v247, v204, v126
	v_fma_f32 v126, v205, v122, v247
	v_fma_f32 v122, v204, v122, -v246
	v_mul_f32_e32 v246, v207, v127
	v_mul_f32_e32 v247, v206, v127
	v_fma_f32 v127, v207, v123, v247
	v_fma_f32 v123, v206, v123, -v246
	v_mul_f32_e32 v120, s28, v120
	v_mul_f32_e32 v121, s28, v121
	v_mul_f32_e32 v122, s28, v122
	v_mul_f32_e32 v123, s28, v123
	v_mul_f32_e32 v124, s28, v124
	v_mul_f32_e32 v125, s28, v125
	v_mul_f32_e32 v126, s28, v126
	v_mul_f32_e32 v127, s28, v127
	v_cvt_pk_bf16_f32 v232, v120, v121
	v_cvt_pk_bf16_f32 v233, v122, v123
	v_cvt_pk_bf16_f32 v234, v124, v125
	v_cvt_pk_bf16_f32 v235, v126, v127
	s_nop 1
	v_permlane16_swap_b32_e32 v232, v234
	v_permlane16_swap_b32_e32 v233, v235
	global_store_dwordx4 v[208:209], v[232:235], off
	s_waitcnt lgkmcnt(0)
	ds_read_b128 v[200:203], v194
	ds_read_b128 v[204:207], v194 offset:16
	v_add_f32_e32 v246, v239, v223
	v_fma_f32 v246, v246, s26, v230
	v_rsq_f32_e32 v246, v246
	v_lshl_add_u64 v[208:209], vcc, 0, v[248:249]
	v_mul_f32_e32 v112, v112, v246
	v_mul_f32_e32 v113, v113, v246
	v_mul_f32_e32 v114, v114, v246
	v_mul_f32_e32 v115, v115, v246
	v_mul_f32_e32 v116, v116, v246
	v_mul_f32_e32 v117, v117, v246
	v_mul_f32_e32 v118, v118, v246
	v_mul_f32_e32 v119, v119, v246
	v_mul_f32_e32 v112, v184, v112
	v_mul_f32_e32 v113, v185, v113
	v_mul_f32_e32 v114, v186, v114
	v_mul_f32_e32 v115, v187, v115
	v_mul_f32_e32 v116, v188, v116
	v_mul_f32_e32 v117, v189, v117
	v_mul_f32_e32 v118, v190, v118
	v_mul_f32_e32 v119, v191, v119
	v_mul_f32_e32 v246, v215, v116
	v_mul_f32_e32 v247, v214, v116
	v_fma_f32 v116, v215, v112, v247
	v_fma_f32 v112, v214, v112, -v246
	v_mul_f32_e32 v246, v217, v117
	v_mul_f32_e32 v247, v216, v117
	v_fma_f32 v117, v217, v113, v247
	v_fma_f32 v113, v216, v113, -v246
	v_mul_f32_e32 v246, v219, v118
	v_mul_f32_e32 v247, v218, v118
	v_fma_f32 v118, v219, v114, v247
	v_fma_f32 v114, v218, v114, -v246
	v_mul_f32_e32 v246, v221, v119
	v_mul_f32_e32 v247, v220, v119
	v_fma_f32 v119, v221, v115, v247
	v_fma_f32 v115, v220, v115, -v246
	v_mul_f32_e32 v112, s28, v112
	v_mul_f32_e32 v113, s28, v113
	v_mul_f32_e32 v114, s28, v114
	v_mul_f32_e32 v115, s28, v115
	v_mul_f32_e32 v116, s28, v116
	v_mul_f32_e32 v117, s28, v117
	v_mul_f32_e32 v118, s28, v118
	v_mul_f32_e32 v119, s28, v119
	v_cvt_pk_bf16_f32 v32, v112, v113
	v_cvt_pk_bf16_f32 v33, v114, v115
	v_cvt_pk_bf16_f32 v34, v116, v117
	v_cvt_pk_bf16_f32 v35, v118, v119
	s_nop 1
	v_permlane16_swap_b32_e32 v32, v34
	v_permlane16_swap_b32_e32 v33, v35
	global_store_dwordx4 v[248:249], v[32:35], off
	s_waitcnt lgkmcnt(0)
	ds_read_b128 v[214:217], v195
	ds_read_b128 v[218:221], v195 offset:16
	v_add_f32_e32 v246, v240, v224
	v_fma_f32 v246, v246, s26, v230
	v_rsq_f32_e32 v246, v246
	v_lshl_add_u64 v[248:249], vcc, 0, v[208:209]
	v_mul_f32_e32 v104, v104, v246
	v_mul_f32_e32 v105, v105, v246
	v_mul_f32_e32 v106, v106, v246
	v_mul_f32_e32 v107, v107, v246
	v_mul_f32_e32 v108, v108, v246
	v_mul_f32_e32 v109, v109, v246
	v_mul_f32_e32 v110, v110, v246
	v_mul_f32_e32 v111, v111, v246
	v_mul_f32_e32 v104, v184, v104
	v_mul_f32_e32 v105, v185, v105
	v_mul_f32_e32 v106, v186, v106
	v_mul_f32_e32 v107, v187, v107
	v_mul_f32_e32 v108, v188, v108
	v_mul_f32_e32 v109, v189, v109
	v_mul_f32_e32 v110, v190, v110
	v_mul_f32_e32 v111, v191, v111
	v_mul_f32_e32 v246, v201, v108
	v_mul_f32_e32 v247, v200, v108
	v_fma_f32 v108, v201, v104, v247
	v_fma_f32 v104, v200, v104, -v246
	v_mul_f32_e32 v246, v203, v109
	v_mul_f32_e32 v247, v202, v109
	v_fma_f32 v109, v203, v105, v247
	v_fma_f32 v105, v202, v105, -v246
	v_mul_f32_e32 v246, v205, v110
	v_mul_f32_e32 v247, v204, v110
	v_fma_f32 v110, v205, v106, v247
	v_fma_f32 v106, v204, v106, -v246
	v_mul_f32_e32 v246, v207, v111
	v_mul_f32_e32 v247, v206, v111
	v_fma_f32 v111, v207, v107, v247
	v_fma_f32 v107, v206, v107, -v246
	v_mul_f32_e32 v104, s28, v104
	v_mul_f32_e32 v105, s28, v105
	v_mul_f32_e32 v106, s28, v106
	v_mul_f32_e32 v107, s28, v107
	v_mul_f32_e32 v108, s28, v108
	v_mul_f32_e32 v109, s28, v109
	v_mul_f32_e32 v110, s28, v110
	v_mul_f32_e32 v111, s28, v111
	v_cvt_pk_bf16_f32 v232, v104, v105
	v_cvt_pk_bf16_f32 v233, v106, v107
	v_cvt_pk_bf16_f32 v234, v108, v109
	v_cvt_pk_bf16_f32 v235, v110, v111
	s_nop 1
	v_permlane16_swap_b32_e32 v232, v234
	v_permlane16_swap_b32_e32 v233, v235
	global_store_dwordx4 v[208:209], v[232:235], off
	s_waitcnt lgkmcnt(0)
	ds_read_b128 v[200:203], v196
	ds_read_b128 v[204:207], v196 offset:16
	v_add_f32_e32 v246, v241, v225
	v_fma_f32 v246, v246, s26, v230
	v_rsq_f32_e32 v246, v246
	s_mov_b32 vcc_lo, 0x5a000
	v_lshl_add_u64 v[208:209], vcc, 0, v[248:249]
	s_mov_b32 vcc_lo, 0x12000
	v_mul_f32_e32 v96, v96, v246
	v_mul_f32_e32 v97, v97, v246
	v_mul_f32_e32 v98, v98, v246
	v_mul_f32_e32 v99, v99, v246
	v_mul_f32_e32 v100, v100, v246
	v_mul_f32_e32 v101, v101, v246
	v_mul_f32_e32 v102, v102, v246
	v_mul_f32_e32 v103, v103, v246
	v_mul_f32_e32 v96, v184, v96
	v_mul_f32_e32 v97, v185, v97
	v_mul_f32_e32 v98, v186, v98
	v_mul_f32_e32 v99, v187, v99
	v_mul_f32_e32 v100, v188, v100
	v_mul_f32_e32 v101, v189, v101
	v_mul_f32_e32 v102, v190, v102
	v_mul_f32_e32 v103, v191, v103
	v_mul_f32_e32 v246, v215, v100
	v_mul_f32_e32 v247, v214, v100
	v_fma_f32 v100, v215, v96, v247
	v_fma_f32 v96, v214, v96, -v246
	v_mul_f32_e32 v246, v217, v101
	v_mul_f32_e32 v247, v216, v101
	v_fma_f32 v101, v217, v97, v247
	v_fma_f32 v97, v216, v97, -v246
	v_mul_f32_e32 v246, v219, v102
	v_mul_f32_e32 v247, v218, v102
	v_fma_f32 v102, v219, v98, v247
	v_fma_f32 v98, v218, v98, -v246
	v_mul_f32_e32 v246, v221, v103
	v_mul_f32_e32 v247, v220, v103
	v_fma_f32 v103, v221, v99, v247
	v_fma_f32 v99, v220, v99, -v246
	v_mul_f32_e32 v96, s28, v96
	v_mul_f32_e32 v97, s28, v97
	v_mul_f32_e32 v98, s28, v98
	v_mul_f32_e32 v99, s28, v99
	v_mul_f32_e32 v100, s28, v100
	v_mul_f32_e32 v101, s28, v101
	v_mul_f32_e32 v102, s28, v102
	v_mul_f32_e32 v103, s28, v103
	v_cvt_pk_bf16_f32 v32, v96, v97
	v_cvt_pk_bf16_f32 v33, v98, v99
	v_cvt_pk_bf16_f32 v34, v100, v101
	v_cvt_pk_bf16_f32 v35, v102, v103
	s_nop 1
	v_permlane16_swap_b32_e32 v32, v34
	v_permlane16_swap_b32_e32 v33, v35
	global_store_dwordx4 v[248:249], v[32:35], off
	s_waitcnt lgkmcnt(0)
	ds_read_b128 v[214:217], v197
	ds_read_b128 v[218:221], v197 offset:16
	v_add_f32_e32 v246, v242, v226
	v_fma_f32 v246, v246, s26, v230
	v_rsq_f32_e32 v246, v246
	v_lshl_add_u64 v[248:249], vcc, 0, v[208:209]
	v_mul_f32_e32 v88, v88, v246
	v_mul_f32_e32 v89, v89, v246
	v_mul_f32_e32 v90, v90, v246
	v_mul_f32_e32 v91, v91, v246
	v_mul_f32_e32 v210, v210, v246
	v_mul_f32_e32 v211, v211, v246
	v_mul_f32_e32 v212, v212, v246
	v_mul_f32_e32 v213, v213, v246
	v_mul_f32_e32 v88, v184, v88
	v_mul_f32_e32 v89, v185, v89
	v_mul_f32_e32 v90, v186, v90
	v_mul_f32_e32 v91, v187, v91
	v_mul_f32_e32 v210, v188, v210
	v_mul_f32_e32 v211, v189, v211
	v_mul_f32_e32 v212, v190, v212
	v_mul_f32_e32 v213, v191, v213
	v_mul_f32_e32 v246, v201, v210
	v_mul_f32_e32 v247, v200, v210
	v_fma_f32 v210, v201, v88, v247
	v_fma_f32 v88, v200, v88, -v246
	v_mul_f32_e32 v246, v203, v211
	v_mul_f32_e32 v247, v202, v211
	v_fma_f32 v211, v203, v89, v247
	v_fma_f32 v89, v202, v89, -v246
	v_mul_f32_e32 v246, v205, v212
	v_mul_f32_e32 v247, v204, v212
	v_fma_f32 v212, v205, v90, v247
	v_fma_f32 v90, v204, v90, -v246
	v_mul_f32_e32 v246, v207, v213
	v_mul_f32_e32 v247, v206, v213
	v_fma_f32 v213, v207, v91, v247
	v_fma_f32 v91, v206, v91, -v246
	v_mul_f32_e32 v88, s28, v88
	v_mul_f32_e32 v89, s28, v89
	v_mul_f32_e32 v90, s28, v90
	v_mul_f32_e32 v91, s28, v91
	v_mul_f32_e32 v210, s28, v210
	v_mul_f32_e32 v211, s28, v211
	v_mul_f32_e32 v212, s28, v212
	v_mul_f32_e32 v213, s28, v213
	v_cvt_pk_bf16_f32 v232, v88, v89
	v_cvt_pk_bf16_f32 v233, v90, v91
	v_cvt_pk_bf16_f32 v234, v210, v211
	v_cvt_pk_bf16_f32 v235, v212, v213
	s_nop 1
	v_permlane16_swap_b32_e32 v232, v234
	v_permlane16_swap_b32_e32 v233, v235
	global_store_dwordx4 v[208:209], v[232:235], off
	s_waitcnt lgkmcnt(0)
	ds_read_b128 v[200:203], v198
	ds_read_b128 v[204:207], v198 offset:16
	v_add_f32_e32 v246, v243, v227
	v_fma_f32 v246, v246, s26, v230
	v_rsq_f32_e32 v246, v246
	v_lshl_add_u64 v[208:209], vcc, 0, v[248:249]
	v_mul_f32_e32 v80, v80, v246
	v_mul_f32_e32 v81, v81, v246
	v_mul_f32_e32 v82, v82, v246
	v_mul_f32_e32 v83, v83, v246
	v_mul_f32_e32 v84, v84, v246
	v_mul_f32_e32 v85, v85, v246
	v_mul_f32_e32 v86, v86, v246
	v_mul_f32_e32 v87, v87, v246
	v_mul_f32_e32 v80, v184, v80
	v_mul_f32_e32 v81, v185, v81
	v_mul_f32_e32 v82, v186, v82
	v_mul_f32_e32 v83, v187, v83
	v_mul_f32_e32 v84, v188, v84
	v_mul_f32_e32 v85, v189, v85
	v_mul_f32_e32 v86, v190, v86
	v_mul_f32_e32 v87, v191, v87
	v_mul_f32_e32 v246, v215, v84
	v_mul_f32_e32 v247, v214, v84
	v_fma_f32 v84, v215, v80, v247
	v_fma_f32 v80, v214, v80, -v246
	v_mul_f32_e32 v246, v217, v85
	v_mul_f32_e32 v247, v216, v85
	v_fma_f32 v85, v217, v81, v247
	v_fma_f32 v81, v216, v81, -v246
	v_mul_f32_e32 v246, v219, v86
	v_mul_f32_e32 v247, v218, v86
	v_fma_f32 v86, v219, v82, v247
	v_fma_f32 v82, v218, v82, -v246
	v_mul_f32_e32 v246, v221, v87
	v_mul_f32_e32 v247, v220, v87
	v_fma_f32 v87, v221, v83, v247
	v_fma_f32 v83, v220, v83, -v246
	v_mul_f32_e32 v80, s28, v80
	v_mul_f32_e32 v81, s28, v81
	v_mul_f32_e32 v82, s28, v82
	v_mul_f32_e32 v83, s28, v83
	v_mul_f32_e32 v84, s28, v84
	v_mul_f32_e32 v85, s28, v85
	v_mul_f32_e32 v86, s28, v86
	v_mul_f32_e32 v87, s28, v87
	v_cvt_pk_bf16_f32 v32, v80, v81
	v_cvt_pk_bf16_f32 v33, v82, v83
	v_cvt_pk_bf16_f32 v34, v84, v85
	v_cvt_pk_bf16_f32 v35, v86, v87
	s_nop 1
	v_permlane16_swap_b32_e32 v32, v34
	v_permlane16_swap_b32_e32 v33, v35
	global_store_dwordx4 v[248:249], v[32:35], off
	s_waitcnt lgkmcnt(0)
	ds_read_b128 v[214:217], v199
	ds_read_b128 v[218:221], v199 offset:16
	v_add_f32_e32 v246, v244, v228
	v_fma_f32 v246, v246, s26, v230
	v_rsq_f32_e32 v246, v246
	v_lshl_add_u64 v[248:249], vcc, 0, v[208:209]
	v_mul_f32_e32 v72, v72, v246
	v_mul_f32_e32 v73, v73, v246
	v_mul_f32_e32 v74, v74, v246
	v_mul_f32_e32 v75, v75, v246
	v_mul_f32_e32 v76, v76, v246
	v_mul_f32_e32 v77, v77, v246
	v_mul_f32_e32 v78, v78, v246
	v_mul_f32_e32 v79, v79, v246
	v_mul_f32_e32 v72, v184, v72
	v_mul_f32_e32 v73, v185, v73
	v_mul_f32_e32 v74, v186, v74
	v_mul_f32_e32 v75, v187, v75
	v_mul_f32_e32 v76, v188, v76
	v_mul_f32_e32 v77, v189, v77
	v_mul_f32_e32 v78, v190, v78
	v_mul_f32_e32 v79, v191, v79
	v_mul_f32_e32 v246, v201, v76
	v_mul_f32_e32 v247, v200, v76
	v_fma_f32 v76, v201, v72, v247
	v_fma_f32 v72, v200, v72, -v246
	v_mul_f32_e32 v246, v203, v77
	v_mul_f32_e32 v247, v202, v77
	v_fma_f32 v77, v203, v73, v247
	v_fma_f32 v73, v202, v73, -v246
	v_mul_f32_e32 v246, v205, v78
	v_mul_f32_e32 v247, v204, v78
	v_fma_f32 v78, v205, v74, v247
	v_fma_f32 v74, v204, v74, -v246
	v_mul_f32_e32 v246, v207, v79
	v_mul_f32_e32 v247, v206, v79
	v_fma_f32 v79, v207, v75, v247
	v_fma_f32 v75, v206, v75, -v246
	v_mul_f32_e32 v72, s28, v72
	v_mul_f32_e32 v73, s28, v73
	v_mul_f32_e32 v74, s28, v74
	v_mul_f32_e32 v75, s28, v75
	v_mul_f32_e32 v76, s28, v76
	v_mul_f32_e32 v77, s28, v77
	v_mul_f32_e32 v78, s28, v78
	v_mul_f32_e32 v79, s28, v79
	v_cvt_pk_bf16_f32 v232, v72, v73
	v_cvt_pk_bf16_f32 v233, v74, v75
	v_cvt_pk_bf16_f32 v234, v76, v77
	v_cvt_pk_bf16_f32 v235, v78, v79
	s_nop 1
	v_permlane16_swap_b32_e32 v232, v234
	v_permlane16_swap_b32_e32 v233, v235
	global_store_dwordx4 v[208:209], v[232:235], off
	s_waitcnt lgkmcnt(0)
	v_add_f32_e32 v246, v245, v229
	v_fma_f32 v246, v246, s26, v230
	v_rsq_f32_e32 v246, v246
	s_nop 0
	v_mul_f32_e32 v64, v64, v246
	v_mul_f32_e32 v65, v65, v246
	v_mul_f32_e32 v66, v66, v246
	v_mul_f32_e32 v67, v67, v246
	v_mul_f32_e32 v68, v68, v246
	v_mul_f32_e32 v69, v69, v246
	v_mul_f32_e32 v70, v70, v246
	v_mul_f32_e32 v71, v71, v246
	v_mul_f32_e32 v64, v184, v64
	v_mul_f32_e32 v65, v185, v65
	v_mul_f32_e32 v66, v186, v66
	v_mul_f32_e32 v67, v187, v67
	v_mul_f32_e32 v68, v188, v68
	v_mul_f32_e32 v69, v189, v69
	v_mul_f32_e32 v70, v190, v70
	v_mul_f32_e32 v71, v191, v71
	v_mul_f32_e32 v246, v215, v68
	v_mul_f32_e32 v247, v214, v68
	v_fma_f32 v68, v215, v64, v247
	v_fma_f32 v64, v214, v64, -v246
	v_mul_f32_e32 v246, v217, v69
	v_mul_f32_e32 v247, v216, v69
	v_fma_f32 v69, v217, v65, v247
	v_fma_f32 v65, v216, v65, -v246
	v_mul_f32_e32 v246, v219, v70
	v_mul_f32_e32 v247, v218, v70
	v_fma_f32 v70, v219, v66, v247
	v_fma_f32 v66, v218, v66, -v246
	v_mul_f32_e32 v246, v221, v71
	v_mul_f32_e32 v247, v220, v71
	v_fma_f32 v71, v221, v67, v247
	v_fma_f32 v67, v220, v67, -v246
	v_mul_f32_e32 v64, s28, v64
	v_mul_f32_e32 v65, s28, v65
	v_mul_f32_e32 v66, s28, v66
	v_mul_f32_e32 v67, s28, v67
	v_mul_f32_e32 v68, s28, v68
	v_mul_f32_e32 v69, s28, v69
	v_mul_f32_e32 v70, s28, v70
	v_mul_f32_e32 v71, s28, v71
	v_cvt_pk_bf16_f32 v32, v64, v65
	v_cvt_pk_bf16_f32 v33, v66, v67
	v_cvt_pk_bf16_f32 v34, v68, v69
	v_cvt_pk_bf16_f32 v35, v70, v71
	s_nop 1
	v_permlane16_swap_b32_e32 v32, v34
	v_permlane16_swap_b32_e32 v33, v35
	global_store_dwordx4 v[248:249], v[32:35], off

.LBB0_864:
	s_andn2_b64 vcc, exec, s[0:1]
	s_cbranch_vccnz .LBB0_74
	s_cmpk_lt_i32 s26, 0x400
	s_cselect_b32 s28, 0x3e38aa3b, 1.0
	s_mov_b32 s27, 0x22110
	s_cselect_b32 s27, 0x22010, s27
	s_lshl_b32 s26, s21, 2
	s_add_u32 s27, s27, s26
	v_add_u32_e32 v246, s27, v161
	ds_read_b128 v[184:187], v246
	ds_read_b128 v[188:191], v246 offset:64
	s_lshl_b32 s0, s20, 8
	v_or_b32_e32 v246, s0, v141
	v_bitop3_b32 v247, s0, v231, v141 bitop3:0x36
	v_lshlrev_b32_e32 v246, 2, v246
	v_lshlrev_b32_e32 v247, 2, v247
	v_add_u32_e32 v246, 0xc000, v246
	v_add_u32_e32 v247, 0xc000, v247
	ds_read2_b32 v[222:223], v246 offset0:64 offset1:80
	ds_read2_b32 v[238:239], v247 offset0:64 offset1:80
	ds_read2_b32 v[224:225], v246 offset0:96 offset1:112
	ds_read2_b32 v[240:241], v247 offset0:96 offset1:112
	ds_read2_b32 v[226:227], v246 offset0:192 offset1:208
	ds_read2_b32 v[242:243], v247 offset0:192 offset1:208
	ds_read2_b32 v[228:229], v246 offset0:224 offset1:240
	ds_read2_b32 v[244:245], v247 offset0:224 offset1:240
	s_cmp_lt_i32 s18, 0x8000
	s_movk_i32 s29, 0xfc0
	s_cselect_b32 s29, 0x7c0, s29
	s_cmp_eq_u32 s21, 0
	s_cbranch_scc0 .Lq1_odd
	s_and_b32 s0, s18, s29
	s_lshl_b32 s0, s0, 1
	s_add_i32 s1, s18, 0x80
	s_and_b32 s1, s1, s29
	s_lshl_b32 s1, s1, 1
	v_add_u32_e32 v192, s0, v150
	v_add_u32_e32 v193, s0, v150
	v_add_u32_e32 v194, s0, v150
	v_add_u32_e32 v195, s0, v150
	v_add_u32_e32 v196, s1, v150
	v_add_u32_e32 v197, s1, v150
	v_add_u32_e32 v198, s1, v150
	v_add_u32_e32 v199, s1, v150
	s_branch .Lq1_rows

.Lq1_rows:
	ds_read_b128 v[200:203], v192
	ds_read_b128 v[204:207], v192 offset:16
	v_mul_u32_u24_e32 v246, s33, v146
	v_add3_u32 v246, v246, v138, v136
	s_lshl_b32 s0, s10, 1
	v_add_u32_e32 v246, s0, v246
	v_mov_b32_e32 v209, s93
	v_add_co_u32_e32 v208, vcc, s92, v246
	s_nop 1
	v_addc_co_u32_e32 v209, vcc, 0, v209, vcc
	s_mov_b32 vcc_lo, 0x12000
	s_mov_b32 vcc_hi, 0
	s_mov_b32 s26, 0x3c800000
	s_waitcnt lgkmcnt(0)
	ds_read_b128 v[214:217], v193
	ds_read_b128 v[218:221], v193 offset:16
	v_add_f32_e32 v246, v238, v222
	v_fma_f32 v246, v246, s26, v230
	v_rsq_f32_e32 v246, v246
	v_lshl_add_u64 v[248:249], vcc, 0, v[208:209]
	v_mul_f32_e32 v56, v56, v246
	v_mul_f32_e32 v57, v57, v246
	v_mul_f32_e32 v58, v58, v246
	v_mul_f32_e32 v59, v59, v246
	v_mul_f32_e32 v60, v60, v246
	v_mul_f32_e32 v61, v61, v246
	v_mul_f32_e32 v62, v62, v246
	v_mul_f32_e32 v63, v63, v246
	v_mul_f32_e32 v56, v184, v56
	v_mul_f32_e32 v57, v185, v57
	v_mul_f32_e32 v58, v186, v58
	v_mul_f32_e32 v59, v187, v59
	v_mul_f32_e32 v60, v188, v60
	v_mul_f32_e32 v61, v189, v61
	v_mul_f32_e32 v62, v190, v62
	v_mul_f32_e32 v63, v191, v63
	v_mul_f32_e32 v246, v201, v60
	v_mul_f32_e32 v247, v200, v60
	v_fma_f32 v60, v201, v56, v247
	v_fma_f32 v56, v200, v56, -v246
	v_mul_f32_e32 v246, v203, v61
	v_mul_f32_e32 v247, v202, v61
	v_fma_f32 v61, v203, v57, v247
	v_fma_f32 v57, v202, v57, -v246
	v_mul_f32_e32 v246, v205, v62
	v_mul_f32_e32 v247, v204, v62
	v_fma_f32 v62, v205, v58, v247
	v_fma_f32 v58, v204, v58, -v246
	v_mul_f32_e32 v246, v207, v63
	v_mul_f32_e32 v247, v206, v63
	v_fma_f32 v63, v207, v59, v247
	v_fma_f32 v59, v206, v59, -v246
	v_mul_f32_e32 v56, s28, v56
	v_mul_f32_e32 v57, s28, v57
	v_mul_f32_e32 v58, s28, v58
	v_mul_f32_e32 v59, s28, v59
	v_mul_f32_e32 v60, s28, v60
	v_mul_f32_e32 v61, s28, v61
	v_mul_f32_e32 v62, s28, v62
	v_mul_f32_e32 v63, s28, v63
	v_cvt_pk_bf16_f32 v232, v56, v57
	v_cvt_pk_bf16_f32 v233, v58, v59
	v_cvt_pk_bf16_f32 v234, v60, v61
	v_cvt_pk_bf16_f32 v235, v62, v63
	s_nop 1
	v_permlane16_swap_b32_e32 v232, v234
	v_permlane16_swap_b32_e32 v233, v235
	global_store_dwordx4 v[208:209], v[232:235], off offset:256
	s_waitcnt lgkmcnt(0)
	ds_read_b128 v[200:203], v194
	ds_read_b128 v[204:207], v194 offset:16
	v_add_f32_e32 v246, v239, v223
	v_fma_f32 v246, v246, s26, v230
	v_rsq_f32_e32 v246, v246
	v_lshl_add_u64 v[208:209], vcc, 0, v[248:249]
	v_mul_f32_e32 v48, v48, v246
	v_mul_f32_e32 v49, v49, v246
	v_mul_f32_e32 v50, v50, v246
	v_mul_f32_e32 v51, v51, v246
	v_mul_f32_e32 v52, v52, v246
	v_mul_f32_e32 v53, v53, v246
	v_mul_f32_e32 v54, v54, v246
	v_mul_f32_e32 v55, v55, v246
	v_mul_f32_e32 v48, v184, v48
	v_mul_f32_e32 v49, v185, v49
	v_mul_f32_e32 v50, v186, v50
	v_mul_f32_e32 v51, v187, v51
	v_mul_f32_e32 v52, v188, v52
	v_mul_f32_e32 v53, v189, v53
	v_mul_f32_e32 v54, v190, v54
	v_mul_f32_e32 v55, v191, v55
	v_mul_f32_e32 v246, v215, v52
	v_mul_f32_e32 v247, v214, v52
	v_fma_f32 v52, v215, v48, v247
	v_fma_f32 v48, v214, v48, -v246
	v_mul_f32_e32 v246, v217, v53
	v_mul_f32_e32 v247, v216, v53
	v_fma_f32 v53, v217, v49, v247
	v_fma_f32 v49, v216, v49, -v246
	v_mul_f32_e32 v246, v219, v54
	v_mul_f32_e32 v247, v218, v54
	v_fma_f32 v54, v219, v50, v247
	v_fma_f32 v50, v218, v50, -v246
	v_mul_f32_e32 v246, v221, v55
	v_mul_f32_e32 v247, v220, v55
	v_fma_f32 v55, v221, v51, v247
	v_fma_f32 v51, v220, v51, -v246
	v_mul_f32_e32 v48, s28, v48
	v_mul_f32_e32 v49, s28, v49
	v_mul_f32_e32 v50, s28, v50
	v_mul_f32_e32 v51, s28, v51
	v_mul_f32_e32 v52, s28, v52
	v_mul_f32_e32 v53, s28, v53
	v_mul_f32_e32 v54, s28, v54
	v_mul_f32_e32 v55, s28, v55
	v_cvt_pk_bf16_f32 v32, v48, v49
	v_cvt_pk_bf16_f32 v33, v50, v51
	v_cvt_pk_bf16_f32 v34, v52, v53
	v_cvt_pk_bf16_f32 v35, v54, v55
	s_nop 1
	v_permlane16_swap_b32_e32 v32, v34
	v_permlane16_swap_b32_e32 v33, v35
	global_store_dwordx4 v[248:249], v[32:35], off offset:256
	s_waitcnt lgkmcnt(0)
	ds_read_b128 v[214:217], v195
	ds_read_b128 v[218:221], v195 offset:16
	v_add_f32_e32 v246, v240, v224
	v_fma_f32 v246, v246, s26, v230
	v_rsq_f32_e32 v246, v246
	v_lshl_add_u64 v[248:249], vcc, 0, v[208:209]
	v_mul_f32_e32 v40, v40, v246
	v_mul_f32_e32 v41, v41, v246
	v_mul_f32_e32 v42, v42, v246
	v_mul_f32_e32 v43, v43, v246
	v_mul_f32_e32 v44, v44, v246
	v_mul_f32_e32 v45, v45, v246
	v_mul_f32_e32 v46, v46, v246
	v_mul_f32_e32 v47, v47, v246
	v_mul_f32_e32 v40, v184, v40
	v_mul_f32_e32 v41, v185, v41
	v_mul_f32_e32 v42, v186, v42
	v_mul_f32_e32 v43, v187, v43
	v_mul_f32_e32 v44, v188, v44
	v_mul_f32_e32 v45, v189, v45
	v_mul_f32_e32 v46, v190, v46
	v_mul_f32_e32 v47, v191, v47
	v_mul_f32_e32 v246, v201, v44
	v_mul_f32_e32 v247, v200, v44
	v_fma_f32 v44, v201, v40, v247
	v_fma_f32 v40, v200, v40, -v246
	v_mul_f32_e32 v246, v203, v45
	v_mul_f32_e32 v247, v202, v45
	v_fma_f32 v45, v203, v41, v247
	v_fma_f32 v41, v202, v41, -v246
	v_mul_f32_e32 v246, v205, v46
	v_mul_f32_e32 v247, v204, v46
	v_fma_f32 v46, v205, v42, v247
	v_fma_f32 v42, v204, v42, -v246
	v_mul_f32_e32 v246, v207, v47
	v_mul_f32_e32 v247, v206, v47
	v_fma_f32 v47, v207, v43, v247
	v_fma_f32 v43, v206, v43, -v246
	v_mul_f32_e32 v40, s28, v40
	v_mul_f32_e32 v41, s28, v41
	v_mul_f32_e32 v42, s28, v42
	v_mul_f32_e32 v43, s28, v43
	v_mul_f32_e32 v44, s28, v44
	v_mul_f32_e32 v45, s28, v45
	v_mul_f32_e32 v46, s28, v46
	v_mul_f32_e32 v47, s28, v47
	v_cvt_pk_bf16_f32 v232, v40, v41
	v_cvt_pk_bf16_f32 v233, v42, v43
	v_cvt_pk_bf16_f32 v234, v44, v45
	v_cvt_pk_bf16_f32 v235, v46, v47
	s_nop 1
	v_permlane16_swap_b32_e32 v232, v234
	v_permlane16_swap_b32_e32 v233, v235
	global_store_dwordx4 v[208:209], v[232:235], off offset:256
	s_waitcnt lgkmcnt(0)
	ds_read_b128 v[200:203], v196
	ds_read_b128 v[204:207], v196 offset:16
	v_add_f32_e32 v246, v241, v225
	v_fma_f32 v246, v246, s26, v230
	v_rsq_f32_e32 v246, v246
	s_mov_b32 vcc_lo, 0x5a000
	v_lshl_add_u64 v[208:209], vcc, 0, v[248:249]
	s_mov_b32 vcc_lo, 0x12000
	v_mul_f32_e32 v180, v180, v246
	v_mul_f32_e32 v181, v181, v246
	v_mul_f32_e32 v182, v182, v246
	v_mul_f32_e32 v183, v183, v246
	v_mul_f32_e32 v36, v36, v246
	v_mul_f32_e32 v37, v37, v246
	v_mul_f32_e32 v38, v38, v246
	v_mul_f32_e32 v39, v39, v246
	v_mul_f32_e32 v180, v184, v180
	v_mul_f32_e32 v181, v185, v181
	v_mul_f32_e32 v182, v186, v182
	v_mul_f32_e32 v183, v187, v183
	v_mul_f32_e32 v36, v188, v36
	v_mul_f32_e32 v37, v189, v37
	v_mul_f32_e32 v38, v190, v38
	v_mul_f32_e32 v39, v191, v39
	v_mul_f32_e32 v246, v215, v36
	v_mul_f32_e32 v247, v214, v36
	v_fma_f32 v36, v215, v180, v247
	v_fma_f32 v180, v214, v180, -v246
	v_mul_f32_e32 v246, v217, v37
	v_mul_f32_e32 v247, v216, v37
	v_fma_f32 v37, v217, v181, v247
	v_fma_f32 v181, v216, v181, -v246
	v_mul_f32_e32 v246, v219, v38
	v_mul_f32_e32 v247, v218, v38
	v_fma_f32 v38, v219, v182, v247
	v_fma_f32 v182, v218, v182, -v246
	v_mul_f32_e32 v246, v221, v39
	v_mul_f32_e32 v247, v220, v39
	v_fma_f32 v39, v221, v183, v247
	v_fma_f32 v183, v220, v183, -v246
	v_mul_f32_e32 v180, s28, v180
	v_mul_f32_e32 v181, s28, v181
	v_mul_f32_e32 v182, s28, v182
	v_mul_f32_e32 v183, s28, v183
	v_mul_f32_e32 v36, s28, v36
	v_mul_f32_e32 v37, s28, v37
	v_mul_f32_e32 v38, s28, v38
	v_mul_f32_e32 v39, s28, v39
	v_cvt_pk_bf16_f32 v32, v180, v181
	v_cvt_pk_bf16_f32 v33, v182, v183
	v_cvt_pk_bf16_f32 v34, v36, v37
	v_cvt_pk_bf16_f32 v35, v38, v39
	s_nop 1
	v_permlane16_swap_b32_e32 v32, v34
	v_permlane16_swap_b32_e32 v33, v35
	global_store_dwordx4 v[248:249], v[32:35], off offset:256
	s_waitcnt lgkmcnt(0)
	ds_read_b128 v[214:217], v197
	ds_read_b128 v[218:221], v197 offset:16
	v_add_f32_e32 v246, v242, v226
	v_fma_f32 v246, v246, s26, v230
	v_rsq_f32_e32 v246, v246
	v_lshl_add_u64 v[248:249], vcc, 0, v[208:209]
	v_mul_f32_e32 v24, v24, v246
	v_mul_f32_e32 v25, v25, v246
	v_mul_f32_e32 v26, v26, v246
	v_mul_f32_e32 v27, v27, v246
	v_mul_f32_e32 v28, v28, v246
	v_mul_f32_e32 v29, v29, v246
	v_mul_f32_e32 v30, v30, v246
	v_mul_f32_e32 v31, v31, v246
	v_mul_f32_e32 v24, v184, v24
	v_mul_f32_e32 v25, v185, v25
	v_mul_f32_e32 v26, v186, v26
	v_mul_f32_e32 v27, v187, v27
	v_mul_f32_e32 v28, v188, v28
	v_mul_f32_e32 v29, v189, v29
	v_mul_f32_e32 v30, v190, v30
	v_mul_f32_e32 v31, v191, v31
	v_mul_f32_e32 v246, v201, v28
	v_mul_f32_e32 v247, v200, v28
	v_fma_f32 v28, v201, v24, v247
	v_fma_f32 v24, v200, v24, -v246
	v_mul_f32_e32 v246, v203, v29
	v_mul_f32_e32 v247, v202, v29
	v_fma_f32 v29, v203, v25, v247
	v_fma_f32 v25, v202, v25, -v246
	v_mul_f32_e32 v246, v205, v30
	v_mul_f32_e32 v247, v204, v30
	v_fma_f32 v30, v205, v26, v247
	v_fma_f32 v26, v204, v26, -v246
	v_mul_f32_e32 v246, v207, v31
	v_mul_f32_e32 v247, v206, v31
	v_fma_f32 v31, v207, v27, v247
	v_fma_f32 v27, v206, v27, -v246
	v_mul_f32_e32 v24, s28, v24
	v_mul_f32_e32 v25, s28, v25
	v_mul_f32_e32 v26, s28, v26
	v_mul_f32_e32 v27, s28, v27
	v_mul_f32_e32 v28, s28, v28
	v_mul_f32_e32 v29, s28, v29
	v_mul_f32_e32 v30, s28, v30
	v_mul_f32_e32 v31, s28, v31
	v_cvt_pk_bf16_f32 v232, v24, v25
	v_cvt_pk_bf16_f32 v233, v26, v27
	v_cvt_pk_bf16_f32 v234, v28, v29
	v_cvt_pk_bf16_f32 v235, v30, v31
	s_nop 1
	v_permlane16_swap_b32_e32 v232, v234
	v_permlane16_swap_b32_e32 v233, v235
	global_store_dwordx4 v[208:209], v[232:235], off offset:256
	s_waitcnt lgkmcnt(0)
	ds_read_b128 v[200:203], v198
	ds_read_b128 v[204:207], v198 offset:16
	v_add_f32_e32 v246, v243, v227
	v_fma_f32 v246, v246, s26, v230
	v_rsq_f32_e32 v246, v246
	v_lshl_add_u64 v[208:209], vcc, 0, v[248:249]
	v_mul_f32_e32 v16, v16, v246
	v_mul_f32_e32 v17, v17, v246
	v_mul_f32_e32 v18, v18, v246
	v_mul_f32_e32 v19, v19, v246
	v_mul_f32_e32 v20, v20, v246
	v_mul_f32_e32 v21, v21, v246
	v_mul_f32_e32 v22, v22, v246
	v_mul_f32_e32 v23, v23, v246
	v_mul_f32_e32 v16, v184, v16
	v_mul_f32_e32 v17, v185, v17
	v_mul_f32_e32 v18, v186, v18
	v_mul_f32_e32 v19, v187, v19
	v_mul_f32_e32 v20, v188, v20
	v_mul_f32_e32 v21, v189, v21
	v_mul_f32_e32 v22, v190, v22
	v_mul_f32_e32 v23, v191, v23
	v_mul_f32_e32 v246, v215, v20
	v_mul_f32_e32 v247, v214, v20
	v_fma_f32 v20, v215, v16, v247
	v_fma_f32 v16, v214, v16, -v246
	v_mul_f32_e32 v246, v217, v21
	v_mul_f32_e32 v247, v216, v21
	v_fma_f32 v21, v217, v17, v247
	v_fma_f32 v17, v216, v17, -v246
	v_mul_f32_e32 v246, v219, v22
	v_mul_f32_e32 v247, v218, v22
	v_fma_f32 v22, v219, v18, v247
	v_fma_f32 v18, v218, v18, -v246
	v_mul_f32_e32 v246, v221, v23
	v_mul_f32_e32 v247, v220, v23
	v_fma_f32 v23, v221, v19, v247
	v_fma_f32 v19, v220, v19, -v246
	v_mul_f32_e32 v16, s28, v16
	v_mul_f32_e32 v17, s28, v17
	v_mul_f32_e32 v18, s28, v18
	v_mul_f32_e32 v19, s28, v19
	v_mul_f32_e32 v20, s28, v20
	v_mul_f32_e32 v21, s28, v21
	v_mul_f32_e32 v22, s28, v22
	v_mul_f32_e32 v23, s28, v23
	v_cvt_pk_bf16_f32 v32, v16, v17
	v_cvt_pk_bf16_f32 v33, v18, v19
	v_cvt_pk_bf16_f32 v34, v20, v21
	v_cvt_pk_bf16_f32 v35, v22, v23
	s_nop 1
	v_permlane16_swap_b32_e32 v32, v34
	v_permlane16_swap_b32_e32 v33, v35
	global_store_dwordx4 v[248:249], v[32:35], off offset:256
	s_waitcnt lgkmcnt(0)
	ds_read_b128 v[214:217], v199
	ds_read_b128 v[218:221], v199 offset:16
	v_add_f32_e32 v246, v244, v228
	v_fma_f32 v246, v246, s26, v230
	v_rsq_f32_e32 v246, v246
	v_lshl_add_u64 v[248:249], vcc, 0, v[208:209]
	v_mul_f32_e32 v8, v8, v246
	v_mul_f32_e32 v9, v9, v246
	v_mul_f32_e32 v10, v10, v246
	v_mul_f32_e32 v11, v11, v246
	v_mul_f32_e32 v12, v12, v246
	v_mul_f32_e32 v13, v13, v246
	v_mul_f32_e32 v14, v14, v246
	v_mul_f32_e32 v15, v15, v246
	v_mul_f32_e32 v8, v184, v8
	v_mul_f32_e32 v9, v185, v9
	v_mul_f32_e32 v10, v186, v10
	v_mul_f32_e32 v11, v187, v11
	v_mul_f32_e32 v12, v188, v12
	v_mul_f32_e32 v13, v189, v13
	v_mul_f32_e32 v14, v190, v14
	v_mul_f32_e32 v15, v191, v15
	v_mul_f32_e32 v246, v201, v12
	v_mul_f32_e32 v247, v200, v12
	v_fma_f32 v12, v201, v8, v247
	v_fma_f32 v8, v200, v8, -v246
	v_mul_f32_e32 v246, v203, v13
	v_mul_f32_e32 v247, v202, v13
	v_fma_f32 v13, v203, v9, v247
	v_fma_f32 v9, v202, v9, -v246
	v_mul_f32_e32 v246, v205, v14
	v_mul_f32_e32 v247, v204, v14
	v_fma_f32 v14, v205, v10, v247
	v_fma_f32 v10, v204, v10, -v246
	v_mul_f32_e32 v246, v207, v15
	v_mul_f32_e32 v247, v206, v15
	v_fma_f32 v15, v207, v11, v247
	v_fma_f32 v11, v206, v11, -v246
	v_mul_f32_e32 v8, s28, v8
	v_mul_f32_e32 v9, s28, v9
	v_mul_f32_e32 v10, s28, v10
	v_mul_f32_e32 v11, s28, v11
	v_mul_f32_e32 v12, s28, v12
	v_mul_f32_e32 v13, s28, v13
	v_mul_f32_e32 v14, s28, v14
	v_mul_f32_e32 v15, s28, v15
	v_cvt_pk_bf16_f32 v232, v8, v9
	v_cvt_pk_bf16_f32 v233, v10, v11
	v_cvt_pk_bf16_f32 v234, v12, v13
	v_cvt_pk_bf16_f32 v235, v14, v15
	s_nop 1
	v_permlane16_swap_b32_e32 v232, v234
	v_permlane16_swap_b32_e32 v233, v235
	global_store_dwordx4 v[208:209], v[232:235], off offset:256
	s_waitcnt lgkmcnt(0)
	v_add_f32_e32 v246, v245, v229
	v_fma_f32 v246, v246, s26, v230
	v_rsq_f32_e32 v246, v246
	s_nop 0
	v_mul_f32_e32 v0, v0, v246
	v_mul_f32_e32 v1, v1, v246
	v_mul_f32_e32 v2, v2, v246
	v_mul_f32_e32 v3, v3, v246
	v_mul_f32_e32 v4, v4, v246
	v_mul_f32_e32 v5, v5, v246
	v_mul_f32_e32 v6, v6, v246
	v_mul_f32_e32 v7, v7, v246
	v_mul_f32_e32 v0, v184, v0
	v_mul_f32_e32 v1, v185, v1
	v_mul_f32_e32 v2, v186, v2
	v_mul_f32_e32 v3, v187, v3
	v_mul_f32_e32 v4, v188, v4
	v_mul_f32_e32 v5, v189, v5
	v_mul_f32_e32 v6, v190, v6
	v_mul_f32_e32 v7, v191, v7
	v_mul_f32_e32 v246, v215, v4
	v_mul_f32_e32 v247, v214, v4
	v_fma_f32 v4, v215, v0, v247
	v_fma_f32 v0, v214, v0, -v246
	v_mul_f32_e32 v246, v217, v5
	v_mul_f32_e32 v247, v216, v5
	v_fma_f32 v5, v217, v1, v247
	v_fma_f32 v1, v216, v1, -v246
	v_mul_f32_e32 v246, v219, v6
	v_mul_f32_e32 v247, v218, v6
	v_fma_f32 v6, v219, v2, v247
	v_fma_f32 v2, v218, v2, -v246
	v_mul_f32_e32 v246, v221, v7
	v_mul_f32_e32 v247, v220, v7
	v_fma_f32 v7, v221, v3, v247
	v_fma_f32 v3, v220, v3, -v246
	v_mul_f32_e32 v0, s28, v0
	v_mul_f32_e32 v1, s28, v1
	v_mul_f32_e32 v2, s28, v2
	v_mul_f32_e32 v3, s28, v3
	v_mul_f32_e32 v4, s28, v4
	v_mul_f32_e32 v5, s28, v5
	v_mul_f32_e32 v6, s28, v6
	v_mul_f32_e32 v7, s28, v7
	v_cvt_pk_bf16_f32 v32, v0, v1
	v_cvt_pk_bf16_f32 v33, v2, v3
	v_cvt_pk_bf16_f32 v34, v4, v5
	v_cvt_pk_bf16_f32 v35, v6, v7
	s_nop 1
	v_permlane16_swap_b32_e32 v32, v34
	v_permlane16_swap_b32_e32 v33, v35
	global_store_dwordx4 v[248:249], v[32:35], off offset:256
	s_branch .LBB0_74
